# SG and FFT stage-2 tiles staged row-major with coalesced row reads; MFMA fragments fetched with ds_read_b64_tr_b16 (no b16 scatter transposes)
# speedup vs baseline: 1.0205x; 1.0095x over previous
; __device__ __forceinline__ int otid(int wv) { int t; asm volatile("v_mbcnt_lo_u32_b32 %0, -1, 0\n\tv_mbcnt_hi_u32_b32 %0, -1, %0\n\tv_lshl_add_u32 %0, %1, 6, %0" : "=&v"(t) : "s"(wv)); return t; }
; __device__ __forceinline__ unsigned cvt_pk_bf16(float lo, float hi) { const f2_t v = {lo, hi}; const bf2_t b = __builtin_convertvector(v, bf2_t); return __builtin_bit_cast(unsigned, b); }
; __device__ void sg_phase(int wv, const Params& p, int jl, unsigned char* lds) {
;     const int tid = otid(wv), lane = tid & 63, w = __builtin_amdgcn_readfirstlane(tid >> 6), lr = lane & 15, lq = lane >> 4;
;     bf16_t* uv = (bf16_t*)(p.ws + WS_BIG1);
;     const u64* vss = (const u64*)(p.ws + WS_SS) + (size_t)(9 + jl) * MTOK;
;     constexpr int PW = 136;
;     bf16_t* WsL = (bf16_t*)lds; bf16_t* VTL = WsL + 128 * PW; float* rsL = (float*)(VTL + 128 * PW);
;     for (int unit = blockIdx.x; unit < 2048; unit += gridDim.x) {
;         const int ch = unit >> 3, g = unit & 7, t0 = ch * 128;
;         if (tid < 128) rsL[tid] = 1.0f / sqrtf((float)vss[t0 + tid] * SSKI + EPSN);
;         __syncthreads();
;         const float* ws = p.a_w_s + ((size_t)jl * 8 + g) * 128 * 128;
; #pragma unroll
;         for (int ps = 0; ps < 8; ++ps) { const int idx = tid + ps * NTHR, t = idx >> 5, s4 = (idx & 31) * 4;
;             const f32x4 wv = *(const f32x4*)(ws + t * 128 + s4); const f32x4 r4 = *(const f32x4*)(rsL + s4); const f32x4 x = wv * r4;
;             u32x2 pk; pk.x = cvt_pk_bf16(x[0], x[1]); pk.y = cvt_pk_bf16(x[2], x[3]); *(u32x2*)(WsL + t * PW + s4) = pk; }
; #pragma unroll
;         for (int ps = 0; ps < 4; ++ps) { const int idx = tid + ps * NTHR, s = idx & 127, d8 = (idx >> 7) * 8;
;             const bf16x8 v = *(const bf16x8*)(uv + (size_t)(t0 + s) * 2048 + 1024 + g * 128 + d8);
; #pragma unroll
;             for (int e = 0; e < 8; ++e) VTL[(d8 + e) * PW + s] = (bf16_t)v[e]; }
;         __syncthreads();
;         bf16x8 af[4];
; #pragma unroll
;         for (int kk = 0; kk < 4; ++kk) af[kk] = *(const bf16x8*)(WsL + (16 * w + lr) * PW + 32 * kk + 8 * lq);
;         const int tok = t0 + 16 * w + lr; const float bs = p.a_b_s[((size_t)jl * 8 + g) * 128 + 16 * w + lr];
.LBB0_284:
	s_andn2_b64 vcc, exec, s[74:75]
	s_cbranch_vccnz .LBB0_290
	v_readlane_b32 s4, v254, 9
	v_readlane_b32 s5, v254, 10
	v_mbcnt_lo_u32_b32 v1, -1, 0
	v_mbcnt_hi_u32_b32 v1, -1, v1
	v_lshl_add_u32 v1, s33, 6, v1
	s_andn2_b64 vcc, exec, s[4:5]
	v_readfirstlane_b32 s6, v1
	s_cbranch_vccnz .LBB0_290
	s_and_b64 s[4:5], s[8:9], exec
	s_mov_b32 s4, 0x280000
	s_cselect_b32 s4, s4, 0x240000
	s_add_u32 s10, s30, s4
	s_addc_u32 s11, s31, 0
	s_and_b64 s[14:15], s[8:9], exec
	v_add_u32_e32 v30, 0xc00, v1
	v_bfe_u32 v3, v1, 4, 2
	s_movk_i32 s14, 0x110
	v_ashrrev_i32_e32 v32, 5, v30
	v_lshlrev_b32_e32 v8, 4, v3
	v_lshlrev_b32_e32 v53, 2, v3
	v_ashrrev_i32_e32 v3, 5, v1
	v_lshlrev_b32_e32 v30, 7, v32
	v_mul_lo_u32 v46, v32, s14
	v_add_u32_e32 v32, 0xe00, v1
	v_lshlrev_b32_e32 v2, 2, v1
	v_lshlrev_b32_e32 v18, 7, v3
	v_mul_lo_u32 v10, v3, s14
	v_add_u32_e32 v3, 0x200, v1
	v_ashrrev_i32_e32 v34, 5, v32
	v_ashrrev_i32_e32 v36, 4, v1
	v_readlane_b32 s7, v254, 57
	v_and_b32_e32 v5, 0x7c, v2
	v_ashrrev_i32_e32 v11, 5, v3
	v_lshlrev_b32_e32 v32, 7, v34
	v_mul_lo_u32 v48, v34, s14
	v_and_b32_e32 v34, -8, v36
	v_or_b32_e32 v36, 7, v36
	v_ashrrev_i32_e32 v3, 4, v3
	v_add_u32_e32 v47, s7, v2
	v_lshlrev_b32_e32 v2, 2, v5
	v_add_u32_e32 v12, 0x400, v1
	v_mul_lo_u32 v63, v36, s14
	v_and_b32_e32 v36, -8, v3
	v_or_b32_e32 v3, 7, v3
	s_cselect_b32 s20, 0x400, 0
	v_add_u32_e32 v50, s7, v2
	s_ashr_i32 s7, s6, 2
	v_mul_lo_u32 v65, v3, s14
	v_ashrrev_i32_e32 v3, 4, v12
	s_and_b32 s6, s7, -16
	v_add_u32_e32 v14, 0x600, v1
	v_and_b32_e32 v38, -8, v3
	v_or_b32_e32 v3, 7, v3
	v_bfi_b32 v52, -16, s7, v1
	s_ashr_i32 s7, s6, 31
	v_mul_lo_u32 v67, v3, s14
	v_ashrrev_i32_e32 v3, 4, v14
	v_and_b32_e32 v40, -8, v3
	v_or_b32_e32 v3, 7, v3
	s_lshl_b64 s[6:7], s[6:7], 2
	v_and_b32_e32 v4, 15, v1
	v_mul_lo_u32 v69, v3, s14
	v_mov_b32_e32 v3, v0
	s_add_u32 s6, s52, s6
	v_add_u32_e32 v16, 0x800, v1
	v_add_u32_e32 v17, 0xa00, v1
	v_lshl_add_u64 v[42:43], s[50:51], 0, v[2:3]
	s_addc_u32 s7, s53, s7
	v_lshlrev_b32_e32 v2, 2, v4
	v_and_b32_e32 v51, 0x7f, v1
	v_mul_lo_u32 v7, v52, s14
	v_ashrrev_i32_e32 v13, 5, v12
	v_ashrrev_i32_e32 v15, 5, v14
	v_ashrrev_i32_e32 v16, 5, v16
	v_ashrrev_i32_e32 v17, 5, v17
	v_lshl_add_u64 v[44:45], s[6:7], 0, v[2:3]
	s_lshl_b32 s6, s20, 2
	s_movk_i32 s4, 0x80
	v_lshl_add_u32 v5, v5, 1, 0
	v_lshl_add_u32 v6, v51, 1, 0
	v_add_u32_e32 v7, 0, v7
	v_add_u32_e32 v9, 0, v8
	v_lshlrev_b32_e32 v20, 7, v11
	v_mul_lo_u32 v11, v11, s14
	v_lshlrev_b32_e32 v22, 7, v13
	v_mul_lo_u32 v13, v13, s14
	v_lshlrev_b32_e32 v24, 7, v15
	v_mul_lo_u32 v15, v15, s14
	v_lshlrev_b32_e32 v26, 7, v16
	v_mul_lo_u32 v16, v16, s14
	v_lshlrev_b32_e32 v28, 7, v17
	v_mul_lo_u32 v17, v17, s14
	v_mul_lo_u32 v49, v34, s14
	v_mul_lo_u32 v64, v36, s14
	v_mul_lo_u32 v12, v38, s14
	v_mul_lo_u32 v14, v40, s14
	v_mul_u32_u24_e32 v71, 0x110, v4
	s_add_u32 s14, s48, s6
	v_cmp_gt_i32_e64 s[4:5], s4, v1
	v_ashrrev_i32_e32 v19, 31, v18
	v_ashrrev_i32_e32 v21, 31, v20
	v_ashrrev_i32_e32 v23, 31, v22
	v_ashrrev_i32_e32 v25, 31, v24
	v_ashrrev_i32_e32 v27, 31, v26
	v_ashrrev_i32_e32 v29, 31, v28
	v_ashrrev_i32_e32 v31, 31, v30
	v_ashrrev_i32_e32 v33, 31, v32
	v_ashrrev_i32_e32 v35, 31, v34
	v_ashrrev_i32_e32 v37, 31, v36
	v_ashrrev_i32_e32 v39, 31, v38
	v_ashrrev_i32_e32 v41, 31, v40
	s_addc_u32 s15, s49, 0
	v_add_u32_e32 v54, v5, v10
	v_add_u32_e32 v55, v5, v11
	v_add_u32_e32 v56, v5, v13
	v_add_u32_e32 v57, v5, v15
	v_add_u32_e32 v58, v5, v16
	v_add_u32_e32 v59, v5, v17
	v_add_u32_e32 v60, v5, v46
	v_add_u32_e32 v61, v5, v48
	v_add_u32_e32 v62, v6, v49
	v_add_u32_e32 v63, v6, v63
	v_add_u32_e32 v64, v6, v64
	v_add_u32_e32 v65, v6, v65
	v_add_u32_e32 v66, v6, v12
	v_add_u32_e32 v67, v6, v67
	v_add_u32_e32 v68, v6, v14
	v_add_u32_e32 v69, v6, v69
	v_add_u32_e32 v70, v7, v8
	v_add_u32_e32 v71, v9, v71
	v_readlane_b32 s21, v254, 41
	v_readlane_b32 s22, v254, 40
	s_mov_b32 s23, s2
	v_mbcnt_lo_u32_b32 v222, -1, 0
	v_mbcnt_hi_u32_b32 v222, -1, v222
	v_lshl_add_u32 v223, s33, 6, v222
	v_lshrrev_b32_e32 v224, 4, v223
	v_and_b32_e32 v225, 15, v223
	v_and_b32_e32 v226, 3, v224
	v_lshlrev_b32_e32 v226, 2, v226
	v_bfe_u32 v227, v224, 2, 2
	v_or_b32_e32 v226, v226, v227
	v_xor_b32_e32 v226, v225, v226
	v_lshlrev_b32_e32 v226, 4, v226
	v_lshl_add_u32 v212, v224, 8, v226
	v_add_u32_e32 v212, 0x8800, v212
	v_lshlrev_b32_e32 v214, 12, v224
	v_lshl_add_u32 v214, v225, 4, v214
	v_mov_b32_e32 v215, 0
	v_lshl_add_u64 v[214:215], s[76:77], 0, v[214:215]
	v_bfe_u32 v224, v222, 2, 2
	v_and_b32_e32 v225, 3, v222
	v_lshrrev_b32_e32 v226, 4, v222
	v_lshl_add_u32 v227, v226, 3, v224
	v_lshlrev_b32_e32 v228, 2, v224
	v_lshlrev_b32_e32 v226, 1, v226
	v_and_b32_e32 v229, 3, v226
	v_or_b32_e32 v229, v228, v229
	v_add_u32_e32 v226, 1, v226
	v_and_b32_e32 v226, 3, v226
	v_or_b32_e32 v226, v228, v226
	v_lshrrev_b32_e32 v228, 1, v225
	v_and_b32_e32 v225, 1, v225
	v_lshlrev_b32_e32 v225, 3, v225
	v_xor_b32_e32 v229, v228, v229
	v_lshl_add_u32 v229, v229, 4, v225
	v_lshl_add_u32 v218, v227, 8, v229
	v_add_u32_e32 v218, 0x8800, v218
	v_xor_b32_e32 v226, v228, v226
	v_lshl_add_u32 v226, v226, 4, v225
	v_add_u32_e32 v227, 4, v227
	v_lshl_add_u32 v219, v227, 8, v226
	v_add_u32_e32 v219, 0x8800, v219
	s_branch .LBB0_288
; __device__ __forceinline__ unsigned cvt_pk_bf16(float lo, float hi) { const f2_t v = {lo, hi}; const bf2_t b = __builtin_convertvector(v, bf2_t); return __builtin_bit_cast(unsigned, b); }
; __device__ void sg_phase(int wv, const Params& p, int jl, unsigned char* lds) {
;     ...
;     for (int unit = blockIdx.x; unit < 2048; unit += gridDim.x) {
;         const int ch = unit >> 3, g = unit & 7, t0 = ch * 128;
;         if (tid < 128) rsL[tid] = 1.0f / sqrtf((float)vss[t0 + tid] * SSKI + EPSN);
;         __syncthreads();
;         const float* ws = p.a_w_s + ((size_t)jl * 8 + g) * 128 * 128;
; #pragma unroll
;         for (int ps = 0; ps < 8; ++ps) { const int idx = tid + ps * NTHR, t = idx >> 5, s4 = (idx & 31) * 4;
;             const f32x4 wv = *(const f32x4*)(ws + t * 128 + s4); const f32x4 r4 = *(const f32x4*)(rsL + s4); const f32x4 x = wv * r4;
;             u32x2 pk; pk.x = cvt_pk_bf16(x[0], x[1]); pk.y = cvt_pk_bf16(x[2], x[3]); *(u32x2*)(WsL + t * PW + s4) = pk; }
; #pragma unroll
;         for (int ps = 0; ps < 4; ++ps) { const int idx = tid + ps * NTHR, s = idx & 127, d8 = (idx >> 7) * 8;
;             const bf16x8 v = *(const bf16x8*)(uv + (size_t)(t0 + s) * 2048 + 1024 + g * 128 + d8);
; #pragma unroll
;             for (int e = 0; e < 8; ++e) VTL[(d8 + e) * PW + s] = (bf16_t)v[e]; }
;         __syncthreads();
.LBB0_287:
	s_or_b64 exec, exec, s[16:17]
	s_and_b32 s6, s22, 0x380
	s_or_b32 s7, s20, s6
	s_lshl_b32 s36, s7, 9
	v_lshl_add_u64 v[10:11], v[42:43], 0, s[36:37]
	v_lshl_add_u64 v[84:85], v[18:19], 2, v[10:11]
	global_load_dwordx4 v[100:103], v[84:85], off
	v_lshl_add_u64 v[86:87], v[20:21], 2, v[10:11]
	global_load_dwordx4 v[104:107], v[86:87], off
	v_lshl_add_u64 v[88:89], v[22:23], 2, v[10:11]
	global_load_dwordx4 v[108:111], v[88:89], off
	v_lshl_add_u64 v[90:91], v[24:25], 2, v[10:11]
	global_load_dwordx4 v[112:115], v[90:91], off
	v_lshl_add_u64 v[92:93], v[26:27], 2, v[10:11]
	global_load_dwordx4 v[116:119], v[92:93], off
	v_lshl_add_u64 v[94:95], v[28:29], 2, v[10:11]
	global_load_dwordx4 v[120:123], v[94:95], off
	v_lshl_add_u64 v[96:97], v[30:31], 2, v[10:11]
	global_load_dwordx4 v[124:127], v[96:97], off
	v_lshl_add_u64 v[98:99], v[32:33], 2, v[10:11]
	global_load_dwordx4 v[128:131], v[98:99], off
	s_lshl_b32 s36, s6, 1
	v_add_u32_e32 v48, s42, v52
	v_ashrrev_i32_e32 v49, 31, v48
	v_or_b32_e32 v82, s6, v53
	v_lshlrev_b64 v[48:49], 12, v[48:49]
	v_lshl_add_u64 v[48:49], s[76:77], 0, v[48:49]
	v_mov_b32_e32 v83, v0
	v_or_b32_e32 v2, s42, v51
	v_ashrrev_i32_e32 v3, 31, v2
	v_lshlrev_b64 v[2:3], 12, v[2:3]
	v_lshl_add_u64 v[2:3], s[76:77], 0, v[2:3]
	v_lshl_add_u64 v[6:7], v[2:3], 0, s[36:37]
	s_lshl_b32 s16, s42, 12
	s_add_u32 s16, s16, s36
	s_mov_b32 s17, 0
	v_lshl_add_u64 v[132:133], v[214:215], 0, s[16:17]
	s_mov_b64 s[16:17], 0x20000
	global_load_dwordx4 v[140:143], v[132:133], off offset:2048
	v_lshl_add_u64 v[132:133], v[132:133], 0, s[16:17]
	global_load_dwordx4 v[144:147], v[132:133], off offset:2048
	v_lshl_add_u64 v[132:133], v[132:133], 0, s[16:17]
	global_load_dwordx4 v[148:151], v[132:133], off offset:2048
	v_lshl_add_u64 v[132:133], v[132:133], 0, s[16:17]
	global_load_dwordx4 v[152:155], v[132:133], off offset:2048
	s_lshl_b32 s36, s7, 2
	v_lshl_add_u64 v[72:73], v[44:45], 0, s[36:37]
	global_load_dword v46, v[72:73], off
	v_lshlrev_b32_e32 v72, 2, v82
	v_lshlrev_b32_e32 v82, 1, v82
	v_lshl_add_u64 v[48:49], v[48:49], 0, v[82:83]
	global_load_dwordx4 v[180:183], v72, s[14:15]
	global_load_dwordx2 v[156:157], v[48:49], off
	global_load_dwordx4 v[184:187], v72, s[14:15] offset:64
	global_load_dwordx2 v[158:159], v[48:49], off offset:32
	global_load_dwordx4 v[188:191], v72, s[14:15] offset:128
	global_load_dwordx2 v[160:161], v[48:49], off offset:64
	global_load_dwordx4 v[192:195], v72, s[14:15] offset:192
	global_load_dwordx2 v[162:163], v[48:49], off offset:96
	global_load_dwordx4 v[196:199], v72, s[14:15] offset:256
	global_load_dwordx2 v[164:165], v[48:49], off offset:128
	global_load_dwordx4 v[200:203], v72, s[14:15] offset:320
	global_load_dwordx2 v[166:167], v[48:49], off offset:160
	global_load_dwordx4 v[204:207], v72, s[14:15] offset:384
	global_load_dwordx2 v[168:169], v[48:49], off offset:192
	global_load_dwordx4 v[208:211], v72, s[14:15] offset:448
	global_load_dwordx2 v[170:171], v[48:49], off offset:224
	v_readlane_b32 s6, v254, 42
	s_add_i32 s23, s23, s34
	s_add_i32 s22, s22, s92
	s_add_i32 s21, s21, s6
	s_cmpk_lt_i32 s23, 0x800
	s_waitcnt lgkmcnt(0)
	s_barrier
	ds_read_b128 v[6:9], v50
	s_waitcnt vmcnt(21) lgkmcnt(0)
	v_pk_mul_f32 v[102:103], v[102:103], v[8:9]
	v_pk_mul_f32 v[100:101], v[100:101], v[6:7]
	v_pk_mul_f32 v[106:107], v[106:107], v[8:9]
	v_pk_mul_f32 v[104:105], v[104:105], v[6:7]
	v_pk_mul_f32 v[110:111], v[110:111], v[8:9]
	v_pk_mul_f32 v[108:109], v[108:109], v[6:7]
	v_pk_mul_f32 v[114:115], v[114:115], v[8:9]
	v_pk_mul_f32 v[112:113], v[112:113], v[6:7]
	v_pk_mul_f32 v[118:119], v[118:119], v[8:9]
	v_pk_mul_f32 v[116:117], v[116:117], v[6:7]
	v_pk_mul_f32 v[122:123], v[122:123], v[8:9]
	v_pk_mul_f32 v[120:121], v[120:121], v[6:7]
	v_pk_mul_f32 v[126:127], v[126:127], v[8:9]
	v_pk_mul_f32 v[124:125], v[124:125], v[6:7]
	v_pk_mul_f32 v[130:131], v[130:131], v[8:9]
	v_pk_mul_f32 v[128:129], v[128:129], v[6:7]
	v_cvt_pk_bf16_f32 v100, v100, v101
	v_cvt_pk_bf16_f32 v101, v102, v103
	v_cvt_pk_bf16_f32 v104, v104, v105
	v_cvt_pk_bf16_f32 v105, v106, v107
	v_cvt_pk_bf16_f32 v108, v108, v109
	v_cvt_pk_bf16_f32 v109, v110, v111
	v_cvt_pk_bf16_f32 v112, v112, v113
	v_cvt_pk_bf16_f32 v113, v114, v115
	v_cvt_pk_bf16_f32 v116, v116, v117
	v_cvt_pk_bf16_f32 v117, v118, v119
	v_cvt_pk_bf16_f32 v120, v120, v121
	v_cvt_pk_bf16_f32 v121, v122, v123
	v_cvt_pk_bf16_f32 v124, v124, v125
	v_cvt_pk_bf16_f32 v125, v126, v127
	v_cvt_pk_bf16_f32 v128, v128, v129
	v_cvt_pk_bf16_f32 v129, v130, v131
	ds_write_b64 v54, v[100:101]
	ds_write_b64 v55, v[104:105]
	ds_write_b64 v56, v[108:109]
	ds_write_b64 v57, v[112:113]
	ds_write_b64 v58, v[116:117]
	ds_write_b64 v59, v[120:121]
	ds_write_b64 v60, v[124:125]
	ds_write_b64 v61, v[128:129]
	s_waitcnt vmcnt(17)
	ds_write_b128 v212, v[140:143]
	ds_write_b128 v212, v[144:147] offset:8192
	ds_write_b128 v212, v[148:151] offset:16384
	ds_write_b128 v212, v[152:155] offset:24576
	s_waitcnt lgkmcnt(0)
	s_barrier
; __device__ __forceinline__ unsigned cvt_pk_bf16(float lo, float hi) { const f2_t v = {lo, hi}; const bf2_t b = __builtin_convertvector(v, bf2_t); return __builtin_bit_cast(unsigned, b); }
; __device__ __forceinline__ f32x4 mfma16(bf16x8 a, bf16x8 b, f32x4 c) { return __builtin_amdgcn_mfma_f32_16x16x32_bf16(a, b, c, 0, 0, 0); }
; __device__ void sg_phase(int wv, const Params& p, int jl, unsigned char* lds) {
;     ...
;         bf16x8 af[4];
; #pragma unroll
;         for (int kk = 0; kk < 4; ++kk) af[kk] = *(const bf16x8*)(WsL + (16 * w + lr) * PW + 32 * kk + 8 * lq);
;         const int tok = t0 + 16 * w + lr; const float bs = p.a_b_s[((size_t)jl * 8 + g) * 128 + 16 * w + lr];
; #pragma unroll
;         for (int db = 0; db < 8; ++db) { f32x4 acc = {0, 0, 0, 0};
; #pragma unroll
;             for (int kk = 0; kk < 4; ++kk) { const bf16x8 bf = *(const bf16x8*)(VTL + (16 * db + lr) * PW + 32 * kk + 8 * lq); acc = mfma16(bf, af[kk], acc); }
;             const int col = g * 128 + 16 * db + 4 * lq; const f32x4 gv = *(const f32x4*)(p.a_g_v + jl * DM + col);
;             bf16_t* up = uv + (size_t)tok * 2048 + col; const u32x2 uu = *(const u32x2*)up;
;             const float u0 = __uint_as_float(uu.x << 16), u1 = __uint_as_float(uu.x & 0xffff0000u), u2 = __uint_as_float(uu.y << 16), u3 = __uint_as_float(uu.y & 0xffff0000u);
;             const f32x4 sv = acc * gv + bs; u32x2 o; o.x = cvt_pk_bf16(u0 * sv[0], u1 * sv[1]); o.y = cvt_pk_bf16(u2 * sv[2], u3 * sv[3]);
;             *(u32x2*)up = o; }
	ds_read_b128 v[14:17], v70
	ds_read_b128 v[10:13], v70 offset:64
	ds_read_b128 v[6:9], v70 offset:128
	ds_read_b128 v[2:5], v70 offset:192
	v_mov_b32_e32 v220, v218
	v_mov_b32_e32 v221, v219
	ds_read_b64_tr_b16 v[72:73], v220
	ds_read_b64_tr_b16 v[74:75], v221
	ds_read_b64_tr_b16 v[76:77], v220 offset:8192
	ds_read_b64_tr_b16 v[78:79], v221 offset:8192
	s_waitcnt lgkmcnt(2)
	v_mfma_f32_16x16x32_bf16 v[72:75], v[72:75], v[14:17], 0
	s_waitcnt lgkmcnt(0)
	v_mfma_f32_16x16x32_bf16 v[72:75], v[76:79], v[10:13], v[72:75]
	ds_read_b64_tr_b16 v[76:77], v220 offset:16384
	ds_read_b64_tr_b16 v[78:79], v221 offset:16384
	s_waitcnt lgkmcnt(0)
	v_mfma_f32_16x16x32_bf16 v[72:75], v[76:79], v[6:9], v[72:75]
	ds_read_b64_tr_b16 v[76:77], v220 offset:24576
	ds_read_b64_tr_b16 v[78:79], v221 offset:24576
	s_waitcnt lgkmcnt(0)
	v_mfma_f32_16x16x32_bf16 v[74:77], v[76:79], v[2:5], v[72:75]
	s_nop 4
	s_waitcnt vmcnt(14)
	s_nop 7
	v_pk_fma_f32 v[74:75], v[74:75], v[180:181], v[46:47] op_sel_hi:[1,1,0]
	v_lshlrev_b32_e32 v78, 16, v156
	v_and_b32_e32 v79, 0xffff0000, v156
	v_pk_fma_f32 v[76:77], v[76:77], v[182:183], v[46:47] op_sel_hi:[1,1,0]
	v_pk_mul_f32 v[74:75], v[74:75], v[78:79]
	v_lshlrev_b32_e32 v78, 16, v157
	v_and_b32_e32 v79, 0xffff0000, v157
	v_pk_mul_f32 v[76:77], v[76:77], v[78:79]
	v_cvt_pk_bf16_f32 v74, v74, v75
	v_cvt_pk_bf16_f32 v75, v76, v77
	global_store_dwordx2 v[48:49], v[74:75], off
	v_xor_b32_e32 v220, 0x20, v218
	v_xor_b32_e32 v221, 0x20, v219
	ds_read_b64_tr_b16 v[74:75], v220
	ds_read_b64_tr_b16 v[76:77], v221
	ds_read_b64_tr_b16 v[78:79], v220 offset:8192
	ds_read_b64_tr_b16 v[80:81], v221 offset:8192
	s_waitcnt lgkmcnt(2)
	v_mfma_f32_16x16x32_bf16 v[74:77], v[74:77], v[14:17], 0
	s_waitcnt lgkmcnt(0)
	v_mfma_f32_16x16x32_bf16 v[74:77], v[78:81], v[10:13], v[74:77]
	ds_read_b64_tr_b16 v[78:79], v220 offset:16384
	ds_read_b64_tr_b16 v[80:81], v221 offset:16384
	s_waitcnt lgkmcnt(0)
	v_mfma_f32_16x16x32_bf16 v[74:77], v[78:81], v[6:9], v[74:77]
	ds_read_b64_tr_b16 v[78:79], v220 offset:24576
	ds_read_b64_tr_b16 v[80:81], v221 offset:24576
	s_waitcnt lgkmcnt(0)
	v_mfma_f32_16x16x32_bf16 v[74:77], v[78:81], v[2:5], v[74:77]
	s_waitcnt vmcnt(13)
	s_nop 7
	s_nop 4
	v_pk_fma_f32 v[74:75], v[74:75], v[184:185], v[46:47] op_sel_hi:[1,1,0]
	v_lshlrev_b32_e32 v78, 16, v158
	v_and_b32_e32 v79, 0xffff0000, v158
	v_pk_fma_f32 v[76:77], v[76:77], v[186:187], v[46:47] op_sel_hi:[1,1,0]
	v_pk_mul_f32 v[74:75], v[74:75], v[78:79]
	v_lshlrev_b32_e32 v78, 16, v159
	v_and_b32_e32 v79, 0xffff0000, v159
	v_pk_mul_f32 v[76:77], v[76:77], v[78:79]
	v_cvt_pk_bf16_f32 v74, v74, v75
	v_cvt_pk_bf16_f32 v75, v76, v77
	global_store_dwordx2 v[48:49], v[74:75], off offset:32
	v_xor_b32_e32 v220, 0x40, v218
	v_xor_b32_e32 v221, 0x40, v219
	ds_read_b64_tr_b16 v[74:75], v220
	ds_read_b64_tr_b16 v[76:77], v221
	ds_read_b64_tr_b16 v[78:79], v220 offset:8192
	ds_read_b64_tr_b16 v[80:81], v221 offset:8192
	s_waitcnt lgkmcnt(2)
	v_mfma_f32_16x16x32_bf16 v[74:77], v[74:77], v[14:17], 0
	s_waitcnt lgkmcnt(0)
	v_mfma_f32_16x16x32_bf16 v[74:77], v[78:81], v[10:13], v[74:77]
	ds_read_b64_tr_b16 v[78:79], v220 offset:16384
	ds_read_b64_tr_b16 v[80:81], v221 offset:16384
	s_waitcnt lgkmcnt(0)
	v_mfma_f32_16x16x32_bf16 v[74:77], v[78:81], v[6:9], v[74:77]
	ds_read_b64_tr_b16 v[78:79], v220 offset:24576
	ds_read_b64_tr_b16 v[80:81], v221 offset:24576
	s_waitcnt lgkmcnt(0)
	v_mfma_f32_16x16x32_bf16 v[74:77], v[78:81], v[2:5], v[74:77]
	s_waitcnt vmcnt(12)
	s_nop 7
	s_nop 4
	v_pk_fma_f32 v[74:75], v[74:75], v[188:189], v[46:47] op_sel_hi:[1,1,0]
	v_lshlrev_b32_e32 v78, 16, v160
	v_and_b32_e32 v79, 0xffff0000, v160
	v_pk_fma_f32 v[76:77], v[76:77], v[190:191], v[46:47] op_sel_hi:[1,1,0]
	v_pk_mul_f32 v[74:75], v[74:75], v[78:79]
	v_lshlrev_b32_e32 v78, 16, v161
	v_and_b32_e32 v79, 0xffff0000, v161
	v_pk_mul_f32 v[76:77], v[76:77], v[78:79]
	v_cvt_pk_bf16_f32 v74, v74, v75
	v_cvt_pk_bf16_f32 v75, v76, v77
	global_store_dwordx2 v[48:49], v[74:75], off offset:64
	v_xor_b32_e32 v220, 0x60, v218
	v_xor_b32_e32 v221, 0x60, v219
	ds_read_b64_tr_b16 v[74:75], v220
	ds_read_b64_tr_b16 v[76:77], v221
	ds_read_b64_tr_b16 v[78:79], v220 offset:8192
	ds_read_b64_tr_b16 v[80:81], v221 offset:8192
	s_waitcnt lgkmcnt(2)
	v_mfma_f32_16x16x32_bf16 v[74:77], v[74:77], v[14:17], 0
	s_waitcnt lgkmcnt(0)
	v_mfma_f32_16x16x32_bf16 v[74:77], v[78:81], v[10:13], v[74:77]
	ds_read_b64_tr_b16 v[78:79], v220 offset:16384
	ds_read_b64_tr_b16 v[80:81], v221 offset:16384
	s_waitcnt lgkmcnt(0)
	v_mfma_f32_16x16x32_bf16 v[74:77], v[78:81], v[6:9], v[74:77]
	ds_read_b64_tr_b16 v[78:79], v220 offset:24576
	ds_read_b64_tr_b16 v[80:81], v221 offset:24576
	s_waitcnt lgkmcnt(0)
	v_mfma_f32_16x16x32_bf16 v[74:77], v[78:81], v[2:5], v[74:77]
	s_waitcnt vmcnt(11)
	s_nop 7
	s_nop 4
	v_pk_fma_f32 v[74:75], v[74:75], v[192:193], v[46:47] op_sel_hi:[1,1,0]
	v_lshlrev_b32_e32 v78, 16, v162
	v_and_b32_e32 v79, 0xffff0000, v162
	v_pk_fma_f32 v[76:77], v[76:77], v[194:195], v[46:47] op_sel_hi:[1,1,0]
	v_pk_mul_f32 v[74:75], v[74:75], v[78:79]
	v_lshlrev_b32_e32 v78, 16, v163
	v_and_b32_e32 v79, 0xffff0000, v163
	v_pk_mul_f32 v[76:77], v[76:77], v[78:79]
	v_cvt_pk_bf16_f32 v74, v74, v75
	v_cvt_pk_bf16_f32 v75, v76, v77
	global_store_dwordx2 v[48:49], v[74:75], off offset:96
	v_xor_b32_e32 v220, 0x80, v218
	v_xor_b32_e32 v221, 0x80, v219
	ds_read_b64_tr_b16 v[74:75], v220
	ds_read_b64_tr_b16 v[76:77], v221
	ds_read_b64_tr_b16 v[78:79], v220 offset:8192
	ds_read_b64_tr_b16 v[80:81], v221 offset:8192
	s_waitcnt lgkmcnt(2)
; __device__ __forceinline__ unsigned cvt_pk_bf16(float lo, float hi) { const f2_t v = {lo, hi}; const bf2_t b = __builtin_convertvector(v, bf2_t); return __builtin_bit_cast(unsigned, b); }
; __device__ __forceinline__ f32x4 mfma16(bf16x8 a, bf16x8 b, f32x4 c) { return __builtin_amdgcn_mfma_f32_16x16x32_bf16(a, b, c, 0, 0, 0); }
; __device__ void sg_phase(int wv, const Params& p, int jl, unsigned char* lds) {
;     ...
;         for (int db = 0; db < 8; ++db) { f32x4 acc = {0, 0, 0, 0};
; #pragma unroll
;             for (int kk = 0; kk < 4; ++kk) { const bf16x8 bf = *(const bf16x8*)(VTL + (16 * db + lr) * PW + 32 * kk + 8 * lq); acc = mfma16(bf, af[kk], acc); }
;             const int col = g * 128 + 16 * db + 4 * lq; const f32x4 gv = *(const f32x4*)(p.a_g_v + jl * DM + col);
;             bf16_t* up = uv + (size_t)tok * 2048 + col; const u32x2 uu = *(const u32x2*)up;
;             const float u0 = __uint_as_float(uu.x << 16), u1 = __uint_as_float(uu.x & 0xffff0000u), u2 = __uint_as_float(uu.y << 16), u3 = __uint_as_float(uu.y & 0xffff0000u);
;             const f32x4 sv = acc * gv + bs; u32x2 o; o.x = cvt_pk_bf16(u0 * sv[0], u1 * sv[1]); o.y = cvt_pk_bf16(u2 * sv[2], u3 * sv[3]);
;             *(u32x2*)up = o; }
	v_mfma_f32_16x16x32_bf16 v[74:77], v[74:77], v[14:17], 0
	s_waitcnt lgkmcnt(0)
	v_mfma_f32_16x16x32_bf16 v[74:77], v[78:81], v[10:13], v[74:77]
	ds_read_b64_tr_b16 v[78:79], v220 offset:16384
	ds_read_b64_tr_b16 v[80:81], v221 offset:16384
	s_waitcnt lgkmcnt(0)
	v_mfma_f32_16x16x32_bf16 v[74:77], v[78:81], v[6:9], v[74:77]
	ds_read_b64_tr_b16 v[78:79], v220 offset:24576
	ds_read_b64_tr_b16 v[80:81], v221 offset:24576
	s_waitcnt lgkmcnt(0)
	v_mfma_f32_16x16x32_bf16 v[74:77], v[78:81], v[2:5], v[74:77]
	s_waitcnt vmcnt(10)
	s_nop 7
	s_nop 4
	v_pk_fma_f32 v[74:75], v[74:75], v[196:197], v[46:47] op_sel_hi:[1,1,0]
	v_lshlrev_b32_e32 v78, 16, v164
	v_and_b32_e32 v79, 0xffff0000, v164
	v_pk_fma_f32 v[76:77], v[76:77], v[198:199], v[46:47] op_sel_hi:[1,1,0]
	v_pk_mul_f32 v[74:75], v[74:75], v[78:79]
	v_lshlrev_b32_e32 v78, 16, v165
	v_and_b32_e32 v79, 0xffff0000, v165
	v_pk_mul_f32 v[76:77], v[76:77], v[78:79]
	v_cvt_pk_bf16_f32 v74, v74, v75
	v_cvt_pk_bf16_f32 v75, v76, v77
	global_store_dwordx2 v[48:49], v[74:75], off offset:128
	v_xor_b32_e32 v220, 0xa0, v218
	v_xor_b32_e32 v221, 0xa0, v219
	ds_read_b64_tr_b16 v[74:75], v220
	ds_read_b64_tr_b16 v[76:77], v221
	ds_read_b64_tr_b16 v[78:79], v220 offset:8192
	ds_read_b64_tr_b16 v[80:81], v221 offset:8192
	s_waitcnt lgkmcnt(2)
	v_mfma_f32_16x16x32_bf16 v[74:77], v[74:77], v[14:17], 0
	s_waitcnt lgkmcnt(0)
	v_mfma_f32_16x16x32_bf16 v[74:77], v[78:81], v[10:13], v[74:77]
	ds_read_b64_tr_b16 v[78:79], v220 offset:16384
	ds_read_b64_tr_b16 v[80:81], v221 offset:16384
	s_waitcnt lgkmcnt(0)
	v_mfma_f32_16x16x32_bf16 v[74:77], v[78:81], v[6:9], v[74:77]
	ds_read_b64_tr_b16 v[78:79], v220 offset:24576
	ds_read_b64_tr_b16 v[80:81], v221 offset:24576
	s_waitcnt lgkmcnt(0)
	v_mfma_f32_16x16x32_bf16 v[74:77], v[78:81], v[2:5], v[74:77]
	s_waitcnt vmcnt(9)
	s_nop 7
	s_nop 4
	v_pk_fma_f32 v[74:75], v[74:75], v[200:201], v[46:47] op_sel_hi:[1,1,0]
	v_lshlrev_b32_e32 v78, 16, v166
	v_and_b32_e32 v79, 0xffff0000, v166
	v_pk_fma_f32 v[76:77], v[76:77], v[202:203], v[46:47] op_sel_hi:[1,1,0]
	v_pk_mul_f32 v[74:75], v[74:75], v[78:79]
	v_lshlrev_b32_e32 v78, 16, v167
	v_and_b32_e32 v79, 0xffff0000, v167
	v_pk_mul_f32 v[76:77], v[76:77], v[78:79]
	v_cvt_pk_bf16_f32 v74, v74, v75
	v_cvt_pk_bf16_f32 v75, v76, v77
	global_store_dwordx2 v[48:49], v[74:75], off offset:160
	v_xor_b32_e32 v220, 0xc0, v218
	v_xor_b32_e32 v221, 0xc0, v219
	ds_read_b64_tr_b16 v[74:75], v220
	ds_read_b64_tr_b16 v[76:77], v221
	ds_read_b64_tr_b16 v[78:79], v220 offset:8192
	ds_read_b64_tr_b16 v[80:81], v221 offset:8192
	s_waitcnt lgkmcnt(2)
	v_mfma_f32_16x16x32_bf16 v[74:77], v[74:77], v[14:17], 0
	s_waitcnt lgkmcnt(0)
	v_mfma_f32_16x16x32_bf16 v[74:77], v[78:81], v[10:13], v[74:77]
	ds_read_b64_tr_b16 v[78:79], v220 offset:16384
	ds_read_b64_tr_b16 v[80:81], v221 offset:16384
	s_waitcnt lgkmcnt(0)
	v_mfma_f32_16x16x32_bf16 v[74:77], v[78:81], v[6:9], v[74:77]
	ds_read_b64_tr_b16 v[78:79], v220 offset:24576
	ds_read_b64_tr_b16 v[80:81], v221 offset:24576
	s_waitcnt lgkmcnt(0)
	v_mfma_f32_16x16x32_bf16 v[74:77], v[78:81], v[2:5], v[74:77]
	s_waitcnt vmcnt(8)
	s_nop 7
	s_nop 4
	v_pk_fma_f32 v[74:75], v[74:75], v[204:205], v[46:47] op_sel_hi:[1,1,0]
	v_lshlrev_b32_e32 v78, 16, v168
	v_and_b32_e32 v79, 0xffff0000, v168
	v_pk_fma_f32 v[76:77], v[76:77], v[206:207], v[46:47] op_sel_hi:[1,1,0]
	v_pk_mul_f32 v[74:75], v[74:75], v[78:79]
	v_lshlrev_b32_e32 v78, 16, v169
	v_and_b32_e32 v79, 0xffff0000, v169
	v_pk_mul_f32 v[76:77], v[76:77], v[78:79]
	v_cvt_pk_bf16_f32 v74, v74, v75
	v_cvt_pk_bf16_f32 v75, v76, v77
	global_store_dwordx2 v[48:49], v[74:75], off offset:192
	v_xor_b32_e32 v220, 0xe0, v218
	v_xor_b32_e32 v221, 0xe0, v219
	ds_read_b64_tr_b16 v[74:75], v220
	ds_read_b64_tr_b16 v[76:77], v221
	s_waitcnt lgkmcnt(0)
	v_mfma_f32_16x16x32_bf16 v[14:17], v[74:77], v[14:17], 0
	ds_read_b64_tr_b16 v[74:75], v220 offset:8192
	ds_read_b64_tr_b16 v[76:77], v221 offset:8192
	s_waitcnt lgkmcnt(0)
	v_mfma_f32_16x16x32_bf16 v[10:13], v[74:77], v[10:13], v[14:17]
	s_nop 4
	ds_read_b64_tr_b16 v[14:15], v220 offset:16384
	ds_read_b64_tr_b16 v[16:17], v221 offset:16384
	s_waitcnt lgkmcnt(0)
	v_mfma_f32_16x16x32_bf16 v[6:9], v[14:17], v[6:9], v[10:13]
	s_nop 2
	ds_read_b64_tr_b16 v[10:11], v220 offset:24576
	ds_read_b64_tr_b16 v[12:13], v221 offset:24576
	s_waitcnt lgkmcnt(0)
	v_mfma_f32_16x16x32_bf16 v[2:5], v[10:13], v[2:5], v[6:9]
	s_nop 2
	s_waitcnt vmcnt(7)
	s_nop 7
	s_nop 1
	v_pk_fma_f32 v[2:3], v[2:3], v[208:209], v[46:47] op_sel_hi:[1,1,0]
	v_lshlrev_b32_e32 v6, 16, v170
	v_and_b32_e32 v7, 0xffff0000, v170
	v_pk_fma_f32 v[4:5], v[4:5], v[210:211], v[46:47] op_sel_hi:[1,1,0]
	v_pk_mul_f32 v[2:3], v[2:3], v[6:7]
	v_lshlrev_b32_e32 v6, 16, v171
	v_and_b32_e32 v7, 0xffff0000, v171
	v_pk_mul_f32 v[4:5], v[4:5], v[6:7]
	v_cvt_pk_bf16_f32 v2, v2, v3
	v_cvt_pk_bf16_f32 v3, v4, v5
	global_store_dwordx2 v[48:49], v[2:3], off offset:224
	s_barrier
	s_cbranch_scc0 .LBB0_290

; __device__ __forceinline__ int otid(int wv) { int t; asm volatile("v_mbcnt_lo_u32_b32 %0, -1, 0\n\tv_mbcnt_hi_u32_b32 %0, -1, %0\n\tv_lshl_add_u32 %0, %1, 6, %0" : "=&v"(t) : "s"(wv)); return t; }
; __device__ void fft2_phase(int wv, const Params& p, unsigned char* lds) {
;     const int tid = otid(wv), lane = tid & 63, w = __builtin_amdgcn_readfirstlane(tid >> 6), lr = lane & 15, lq = lane >> 4;
;     constexpr int PW = 136;
;     const bf16_t* A1 = (const bf16_t*)(p.ws + WS_BIG2); bf16_t* Y = (bf16_t*)(p.ws + WS_BIG1);
;     const bf16_t* ctg = (const bf16_t*)(p.ws + WS_TAB + TAB_CT128); const bf16_t* stg = (const bf16_t*)(p.ws + WS_TAB + TAB_ST128);
;     bf16_t* CT = (bf16_t*)lds; bf16_t* ST = CT + 128 * PW; bf16_t* XR = ST + 128 * PW; bf16_t* XI = XR + 128 * PW;
;     for (int idx = tid; idx < 128 * 16; idx += NTHR) { const int r = idx >> 4, c8 = (idx & 15) * 8;
;         *(bf16x8*)(CT + r * PW + c8) = *(const bf16x8*)(ctg + r * 128 + c8); *(bf16x8*)(ST + r * PW + c8) = *(const bf16x8*)(stg + r * 128 + c8); }
;     __syncthreads();
;     for (int unit = blockIdx.x; unit < 2048; unit += gridDim.x) {
;         const int gi = unit >> 3, cb = unit & 7;
;         const int seq = gi < 64 ? 0 : (gi < 128 ? 1 : 2); const int ka = gi - (seq == 0 ? 0 : (seq == 1 ? 64 : 128)); const int N1 = seq == 2 ? 128 : 64;
;         const size_t sbase = (size_t)seq * 8192;
; #pragma unroll
;         for (int ps = 0; ps < 4; ++ps) { const int idx = tid + ps * NTHR, b = idx & 127, c8 = (idx >> 7) * 8;
;             const bf16_t* rp = A1 + ((size_t)gi * 128 + b) * 2048 + cb * 128 + c8; const bf16x8 vr = *(const bf16x8*)rp, vi = *(const bf16x8*)(rp + 1024);
; #pragma unroll
;             for (int e = 0; e < 8; ++e) { XR[(c8 + e) * PW + b] = (bf16_t)vr[e]; XI[(c8 + e) * PW + b] = (bf16_t)vi[e]; } }
;         __syncthreads();
;         bf16x8 xr[4], xi[4], nxr[4];
; #pragma unroll
;         for (int kk = 0; kk < 4; ++kk) { xr[kk] = *(const bf16x8*)(XR + (16 * w + lr) * PW + 32 * kk + 8 * lq); xi[kk] = *(const bf16x8*)(XI + (16 * w + lr) * PW + 32 * kk + 8 * lq);
.LBB0_388:
	s_or_b64 exec, exec, s[0:1]
	v_readlane_b32 s0, v254, 9
	v_readlane_b32 s1, v254, 10
	s_andn2_b64 vcc, exec, s[0:1]
	s_waitcnt lgkmcnt(0)
	s_barrier
	s_cbranch_vccnz .LBB0_391
	v_and_b32_e32 v3, 0x7f, v2
	v_readlane_b32 s0, v254, 13
	v_lshlrev_b32_e32 v4, 12, v3
	v_mov_b32_e32 v5, v0
	v_readlane_b32 s1, v254, 14
	v_bfe_u32 v1, v2, 4, 2
	v_lshlrev_b32_e32 v6, 4, v1
	v_lshl_add_u64 v[52:53], s[0:1], 0, v[4:5]
	s_ashr_i32 s1, s10, 2
	s_and_b32 s0, s1, -16
	v_bfi_b32 v4, -16, s1, v2
	s_movk_i32 s1, 0x110
	v_mul_lo_u32 v5, v4, s1
	s_ashr_i32 s1, s0, 31
	s_lshl_b64 s[0:1], s[0:1], 1
	v_readlane_b32 s6, v254, 57
	v_readlane_b32 s7, v254, 59
	s_add_u32 s0, s76, s0
	v_lshlrev_b32_e32 v4, 3, v1
	v_add3_u32 v1, s6, v5, v6
	v_add3_u32 v80, s7, v5, v6
	s_addc_u32 s1, s77, s1
	v_mov_b32_e32 v5, v0
	v_lshl_add_u64 v[54:55], s[0:1], 0, v[4:5]
	v_ashrrev_i32_e32 v4, 4, v2
	v_and_b32_e32 v56, -8, v4
	s_movk_i32 s0, 0x88
	v_mul_lo_u32 v5, v56, s0
	v_add_lshl_u32 v5, v5, v3, 1
	v_or_b32_e32 v4, 7, v4
	v_add_u32_e32 v7, 0x110, v5
	v_mul_lo_u32 v4, v4, s0
	v_add_u32_e32 v83, s6, v7
	v_add_u32_e32 v84, s7, v7
	v_add_u32_e32 v7, 0x220, v5
	v_add_lshl_u32 v4, v4, v3, 1
	v_add_u32_e32 v85, s6, v7
	v_add_u32_e32 v86, s7, v7
	v_add_u32_e32 v7, 0x330, v5
	v_add_u32_e32 v95, s6, v4
	v_add_u32_e32 v96, s7, v4
	v_add_u32_e32 v4, 0x200, v2
	v_add_u32_e32 v87, s6, v7
	v_add_u32_e32 v88, s7, v7
	v_add_u32_e32 v7, 0x440, v5
	v_ashrrev_i32_e32 v4, 4, v4
	v_add_u32_e32 v81, s6, v5
	v_add_u32_e32 v82, s7, v5
	v_add_u32_e32 v89, s6, v7
	v_add_u32_e32 v90, s7, v7
	v_add_u32_e32 v7, 0x550, v5
	v_add_u32_e32 v5, 0x660, v5
	v_and_b32_e32 v58, -8, v4
	v_add_u32_e32 v93, s6, v5
	v_add_u32_e32 v94, s7, v5
	v_mul_lo_u32 v5, v58, s0
	v_add_lshl_u32 v5, v5, v3, 1
	v_or_b32_e32 v4, 7, v4
	v_add_u32_e32 v91, s6, v7
	v_add_u32_e32 v92, s7, v7
	v_add_u32_e32 v7, 0x110, v5
	v_mul_lo_u32 v4, v4, s0
	v_add_u32_e32 v99, s6, v7
	v_add_u32_e32 v100, s7, v7
	v_add_u32_e32 v7, 0x220, v5
	v_add_lshl_u32 v4, v4, v3, 1
	v_add_u32_e32 v101, s6, v7
	v_add_u32_e32 v102, s7, v7
	v_add_u32_e32 v7, 0x330, v5
	v_add_u32_e32 v111, s6, v4
	v_add_u32_e32 v112, s7, v4
	v_add_u32_e32 v4, 0x400, v2
	v_add_u32_e32 v103, s6, v7
	v_add_u32_e32 v104, s7, v7
	v_add_u32_e32 v7, 0x440, v5
	v_ashrrev_i32_e32 v4, 4, v4
	v_add_u32_e32 v97, s6, v5
	v_add_u32_e32 v98, s7, v5
	v_add_u32_e32 v105, s6, v7
	v_add_u32_e32 v106, s7, v7
	v_add_u32_e32 v7, 0x550, v5
	v_add_u32_e32 v5, 0x660, v5
	v_and_b32_e32 v60, -8, v4
	v_add_u32_e32 v109, s6, v5
	v_add_u32_e32 v110, s7, v5
	v_mul_lo_u32 v5, v60, s0
	v_add_lshl_u32 v5, v5, v3, 1
	v_and_b32_e32 v50, 15, v2
	v_add_u32_e32 v107, s6, v7
	v_add_u32_e32 v108, s7, v7
	v_add_u32_e32 v7, 0x110, v5
	v_or_b32_e32 v4, 7, v4
	v_add_u32_e32 v2, 0x600, v2
	v_add_u32_e32 v115, s6, v7
	v_add_u32_e32 v116, s7, v7
	v_add_u32_e32 v7, 0x220, v5
	v_mul_lo_u32 v4, v4, s0
	v_ashrrev_i32_e32 v2, 4, v2
	v_add_u32_e32 v117, s6, v7
	v_add_u32_e32 v118, s7, v7
	v_add_u32_e32 v7, 0x330, v5
	v_add_lshl_u32 v4, v4, v3, 1
	v_and_b32_e32 v62, -8, v2
	v_add_u32_e32 v119, s6, v7
	v_add_u32_e32 v120, s7, v7
	v_add_u32_e32 v7, 0x440, v5
	v_add_u32_e32 v127, s6, v4
	v_add_u32_e32 v128, s7, v4
	v_mul_lo_u32 v4, v62, s0
	v_add_u32_e32 v113, s6, v5
	v_add_u32_e32 v114, s7, v5
	v_add_u32_e32 v121, s6, v7
	v_add_u32_e32 v122, s7, v7
	v_add_u32_e32 v7, 0x550, v5
	v_add_u32_e32 v5, 0x660, v5
	v_add_lshl_u32 v4, v4, v3, 1
	v_add_u32_e32 v125, s6, v5
	v_add_u32_e32 v126, s7, v5
	v_add_u32_e32 v5, 0x110, v4
	v_or_b32_e32 v2, 7, v2
	v_add_u32_e32 v131, s6, v5
	v_add_u32_e32 v132, s7, v5
	v_add_u32_e32 v5, 0x220, v4
	v_mul_lo_u32 v2, v2, s0
	v_add_u32_e32 v133, s6, v5
	v_add_u32_e32 v134, s7, v5
	v_add_u32_e32 v5, 0x330, v4
	v_add_lshl_u32 v2, v2, v3, 1
	v_add_u32_e32 v135, s6, v5
	v_add_u32_e32 v136, s7, v5
	v_add_u32_e32 v5, 0x440, v4
	v_add_u32_e32 v143, s6, v2
	v_add_u32_e32 v144, s7, v2
	v_mul_u32_u24_e32 v2, 0x88, v50
	v_add_u32_e32 v129, s6, v4
	v_add_u32_e32 v130, s7, v4
	v_add_u32_e32 v137, s6, v5
	v_add_u32_e32 v138, s7, v5
	v_add_u32_e32 v5, 0x550, v4
	v_add_u32_e32 v4, 0x660, v4
	v_lshlrev_b32_e32 v2, 1, v2
	v_ashrrev_i32_e32 v57, 31, v56
	v_ashrrev_i32_e32 v59, 31, v58
	v_ashrrev_i32_e32 v61, 31, v60
	v_add_u32_e32 v123, s6, v7
	v_add_u32_e32 v124, s7, v7
	v_ashrrev_i32_e32 v63, 31, v62
	v_add_u32_e32 v139, s6, v5
	v_add_u32_e32 v140, s7, v5
	v_add_u32_e32 v141, s6, v4
	v_add_u32_e32 v142, s7, v4
	v_add3_u32 v145, 0, v6, v2
	v_mov_b32_e32 v51, v0
	v_or_b32_e32 v64, 16, v50
	v_mov_b32_e32 v65, v0
	v_or_b32_e32 v66, 32, v50
	v_mov_b32_e32 v67, v0
	v_or_b32_e32 v68, 48, v50
	v_mov_b32_e32 v69, v0
	v_or_b32_e32 v70, 64, v50
	v_mov_b32_e32 v71, v0
	v_or_b32_e32 v72, 0x50, v50
	v_mov_b32_e32 v73, v0
	v_or_b32_e32 v74, 0x60, v50
	v_mov_b32_e32 v75, v0
	v_or_b32_e32 v76, 0x70, v50
	v_mov_b32_e32 v77, v0
	v_readlane_b32 s6, v254, 40
	s_mov_b32 s7, s2
	v_mbcnt_lo_u32_b32 v176, -1, 0
	v_mbcnt_hi_u32_b32 v176, -1, v176
	v_lshl_add_u32 v171, s33, 6, v176
	v_lshrrev_b32_e32 v172, 4, v171
	v_and_b32_e32 v173, 15, v171
	v_and_b32_e32 v174, 3, v172
	v_lshlrev_b32_e32 v174, 2, v174
	v_bfe_u32 v175, v172, 2, 2
	v_or_b32_e32 v174, v174, v175
	v_xor_b32_e32 v174, v173, v174
	v_lshlrev_b32_e32 v174, 4, v174
	v_lshl_add_u32 v168, v172, 8, v174
	v_add_u32_e32 v168, 0x11000, v168
	v_lshlrev_b32_e32 v166, 12, v172
	v_lshl_add_u32 v166, v173, 4, v166
	v_mov_b32_e32 v167, 0
	v_readlane_b32 s14, v254, 13
	v_readlane_b32 s15, v254, 14
	s_nop 0
	v_lshl_add_u64 v[166:167], s[14:15], 0, v[166:167]
	v_bfe_u32 v172, v176, 2, 2
	v_and_b32_e32 v173, 3, v176
	v_lshrrev_b32_e32 v174, 4, v176
	v_lshl_add_u32 v175, v174, 3, v172
	v_lshlrev_b32_e32 v177, 2, v172
	v_lshlrev_b32_e32 v174, 1, v174
	v_and_b32_e32 v178, 3, v174
	v_or_b32_e32 v178, v177, v178
	v_add_u32_e32 v174, 1, v174
	v_and_b32_e32 v174, 3, v174
	v_or_b32_e32 v174, v177, v174
	s_lshl_b32 s14, s33, 1
	v_lshrrev_b32_e32 v177, 1, v173
	v_add_u32_e32 v177, s14, v177
	v_and_b32_e32 v173, 1, v173
	v_lshlrev_b32_e32 v173, 3, v173
	v_xor_b32_e32 v178, v177, v178
	v_lshl_add_u32 v178, v178, 4, v173
	v_lshl_add_u32 v169, v175, 8, v178
	v_add_u32_e32 v169, 0x11000, v169
	v_xor_b32_e32 v174, v177, v174
	v_lshl_add_u32 v174, v174, 4, v173
	v_add_u32_e32 v175, 4, v175
	v_lshl_add_u32 v170, v175, 8, v174
	v_add_u32_e32 v170, 0x11000, v170
; __device__ __forceinline__ f32x4 mfma16(bf16x8 a, bf16x8 b, f32x4 c) { return __builtin_amdgcn_mfma_f32_16x16x32_bf16(a, b, c, 0, 0, 0); }
; __device__ void fft2_phase(int wv, const Params& p, unsigned char* lds) {
;     ...
;     for (int unit = blockIdx.x; unit < 2048; unit += gridDim.x) {
;         const int gi = unit >> 3, cb = unit & 7;
;         const int seq = gi < 64 ? 0 : (gi < 128 ? 1 : 2); const int ka = gi - (seq == 0 ? 0 : (seq == 1 ? 64 : 128)); const int N1 = seq == 2 ? 128 : 64;
;         const size_t sbase = (size_t)seq * 8192;
; #pragma unroll
;         for (int ps = 0; ps < 4; ++ps) { const int idx = tid + ps * NTHR, b = idx & 127, c8 = (idx >> 7) * 8;
;             const bf16_t* rp = A1 + ((size_t)gi * 128 + b) * 2048 + cb * 128 + c8; const bf16x8 vr = *(const bf16x8*)rp, vi = *(const bf16x8*)(rp + 1024);
; #pragma unroll
;             for (int e = 0; e < 8; ++e) { XR[(c8 + e) * PW + b] = (bf16_t)vr[e]; XI[(c8 + e) * PW + b] = (bf16_t)vi[e]; } }
;         __syncthreads();
;         bf16x8 xr[4], xi[4], nxr[4];
; #pragma unroll
;         for (int kk = 0; kk < 4; ++kk) { xr[kk] = *(const bf16x8*)(XR + (16 * w + lr) * PW + 32 * kk + 8 * lq); xi[kk] = *(const bf16x8*)(XI + (16 * w + lr) * PW + 32 * kk + 8 * lq);
;             union { bf16x8 v; unsigned u[4]; } t; t.v = xr[kk]; t.u[0] ^= 0x80008000u; t.u[1] ^= 0x80008000u; t.u[2] ^= 0x80008000u; t.u[3] ^= 0x80008000u; nxr[kk] = t.v; }
; #pragma unroll
;         for (int i = 0; i < 8; ++i) { f32x4 re = {0, 0, 0, 0}, im = {0, 0, 0, 0};
; #pragma unroll
;             for (int kk = 0; kk < 4; ++kk) { const bf16x8 cf = *(const bf16x8*)(CT + (16 * i + lr) * PW + 32 * kk + 8 * lq), sf = *(const bf16x8*)(ST + (16 * i + lr) * PW + 32 * kk + 8 * lq);
;                 re = mfma16(xr[kk], cf, re); re = mfma16(xi[kk], sf, re); im = mfma16(xi[kk], cf, im); im = mfma16(nxr[kk], sf, im); }
.LBB0_390:
	s_ashr_i32 s14, s7, 3
	s_cmpk_lt_i32 s14, 0x80
	s_cselect_b32 s0, 1, 2
	s_and_b32 s1, s7, 0xfffffe00
	s_cmpk_eq_i32 s1, 0x200
	s_movk_i32 s1, 0xff80
	s_cselect_b32 s1, 0xffffffc0, s1
	s_cmp_gt_i32 s14, 63
	s_cselect_b32 s10, s0, 0
	s_cselect_b32 s0, s1, 0
	s_ashr_i32 s15, s14, 31
	s_add_i32 s0, s0, s14
	s_lshl_b64 s[14:15], s[14:15], 19
	s_and_b32 s11, s6, 0x380
	v_lshl_add_u64 v[2:3], v[52:53], 0, s[14:15]
	s_lshl_b32 s36, s11, 1
	v_lshl_add_u64 v[2:3], v[2:3], 0, s[36:37]
	v_lshl_add_u64 v[162:163], v[166:167], 0, s[14:15]
	v_lshl_add_u64 v[162:163], v[162:163], 0, s[36:37]
	s_mov_b64 s[14:15], 0x20000
	global_load_dwordx4 v[180:183], v[162:163], off
	global_load_dwordx4 v[184:187], v[162:163], off offset:2048
	v_lshl_add_u64 v[162:163], v[162:163], 0, s[14:15]
	global_load_dwordx4 v[188:191], v[162:163], off
	global_load_dwordx4 v[192:195], v[162:163], off offset:2048
	v_lshl_add_u64 v[162:163], v[162:163], 0, s[14:15]
	global_load_dwordx4 v[196:199], v[162:163], off
	global_load_dwordx4 v[200:203], v[162:163], off offset:2048
	v_lshl_add_u64 v[162:163], v[162:163], 0, s[14:15]
	global_load_dwordx4 v[204:207], v[162:163], off
	global_load_dwordx4 v[208:211], v[162:163], off offset:2048
	s_lshl_b32 s1, s10, 13
	s_ashr_i32 s11, s0, 31
	s_add_u32 s0, s0, s1
	s_addc_u32 s1, s11, 0
	s_cmp_eq_u32 s10, 2
	s_cselect_b32 s10, 7, 6
	v_lshl_add_u64 v[78:79], v[54:55], 0, s[36:37]
	s_add_i32 s7, s7, s34
	s_add_i32 s6, s6, s92
	s_cmpk_lt_i32 s7, 0x800
	s_waitcnt vmcnt(7)
	ds_write_b128 v168, v[180:183] offset:0
	s_waitcnt vmcnt(6)
	ds_write_b128 v168, v[184:187] offset:32768
	s_waitcnt vmcnt(5)
	ds_write_b128 v168, v[188:191] offset:8192
	s_waitcnt vmcnt(4)
	ds_write_b128 v168, v[192:195] offset:40960
	s_waitcnt vmcnt(3)
	ds_write_b128 v168, v[196:199] offset:16384
	s_waitcnt vmcnt(2)
	ds_write_b128 v168, v[200:203] offset:49152
	s_waitcnt vmcnt(1)
	ds_write_b128 v168, v[204:207] offset:24576
	s_waitcnt vmcnt(0)
	ds_write_b128 v168, v[208:211] offset:57344
	s_waitcnt lgkmcnt(0)
	s_barrier
	ds_read_b64_tr_b16 v[46:47], v169 offset:0
	ds_read_b64_tr_b16 v[48:49], v170 offset:0
	ds_read_b64_tr_b16 v[38:39], v169 offset:32768
	ds_read_b64_tr_b16 v[40:41], v170 offset:32768
	ds_read_b64_tr_b16 v[34:35], v169 offset:8192
	ds_read_b64_tr_b16 v[36:37], v170 offset:8192
	ds_read_b64_tr_b16 v[30:31], v169 offset:40960
	ds_read_b64_tr_b16 v[32:33], v170 offset:40960
	ds_read_b64_tr_b16 v[22:23], v169 offset:16384
	ds_read_b64_tr_b16 v[24:25], v170 offset:16384
	ds_read_b64_tr_b16 v[14:15], v169 offset:49152
	ds_read_b64_tr_b16 v[16:17], v170 offset:49152
	s_waitcnt lgkmcnt(9)
	ds_read_b64_tr_b16 v[10:11], v169 offset:24576
	ds_read_b64_tr_b16 v[12:13], v170 offset:24576
	ds_read_b64_tr_b16 v[2:3], v169 offset:57344
	ds_read_b64_tr_b16 v[4:5], v170 offset:57344
	ds_read_b128 v[146:149], v145
	ds_read_b128 v[150:153], v145 offset:34816
	s_waitcnt lgkmcnt(13)
	v_xor_b32_e32 v42, 0x80008000, v46
	v_xor_b32_e32 v43, 0x80008000, v47
	v_xor_b32_e32 v44, 0x80008000, v48
	v_xor_b32_e32 v45, 0x80008000, v49
	s_waitcnt lgkmcnt(1)
	v_mfma_f32_16x16x32_bf16 v[154:157], v[46:49], v[146:149], 0
	v_xor_b32_e32 v26, 0x80008000, v34
	v_xor_b32_e32 v27, 0x80008000, v35
	v_xor_b32_e32 v28, 0x80008000, v36
	v_mfma_f32_16x16x32_bf16 v[146:149], v[38:41], v[146:149], 0
	v_xor_b32_e32 v29, 0x80008000, v37
	v_xor_b32_e32 v18, 0x80008000, v22
	v_xor_b32_e32 v19, 0x80008000, v23
	s_waitcnt lgkmcnt(0)
	v_mfma_f32_16x16x32_bf16 v[154:157], v[38:41], v[150:153], v[154:157]
	v_xor_b32_e32 v20, 0x80008000, v24
	v_xor_b32_e32 v21, 0x80008000, v25
	v_xor_b32_e32 v6, 0x80008000, v10
	v_mfma_f32_16x16x32_bf16 v[146:149], v[42:45], v[150:153], v[146:149]
	ds_read_b128 v[150:153], v145 offset:64
	ds_read_b128 v[158:161], v145 offset:34880
	v_xor_b32_e32 v7, 0x80008000, v11
	v_xor_b32_e32 v8, 0x80008000, v12
	s_waitcnt lgkmcnt(1)
	v_mfma_f32_16x16x32_bf16 v[154:157], v[34:37], v[150:153], v[154:157]
	v_xor_b32_e32 v9, 0x80008000, v13
	v_mfma_f32_16x16x32_bf16 v[146:149], v[30:33], v[150:153], v[146:149]
	s_waitcnt lgkmcnt(0)
	v_mfma_f32_16x16x32_bf16 v[154:157], v[30:33], v[158:161], v[154:157]
	v_mfma_f32_16x16x32_bf16 v[146:149], v[26:29], v[158:161], v[146:149]
	ds_read_b128 v[150:153], v145 offset:128
	ds_read_b128 v[158:161], v145 offset:34944
	s_waitcnt lgkmcnt(1)
	v_mfma_f32_16x16x32_bf16 v[154:157], v[22:25], v[150:153], v[154:157]
	v_mfma_f32_16x16x32_bf16 v[146:149], v[14:17], v[150:153], v[146:149]
	s_waitcnt lgkmcnt(0)
	v_mfma_f32_16x16x32_bf16 v[154:157], v[14:17], v[158:161], v[154:157]
	v_mfma_f32_16x16x32_bf16 v[146:149], v[18:21], v[158:161], v[146:149]
	ds_read_b128 v[150:153], v145 offset:192
	ds_read_b128 v[158:161], v145 offset:35008
	s_waitcnt lgkmcnt(1)
	v_mfma_f32_16x16x32_bf16 v[154:157], v[10:13], v[150:153], v[154:157]
	v_mfma_f32_16x16x32_bf16 v[146:149], v[2:5], v[150:153], v[146:149]
	v_lshlrev_b64 v[150:151], s10, v[50:51]
	v_lshl_add_u64 v[150:151], s[0:1], 0, v[150:151]
	v_lshlrev_b64 v[150:151], 12, v[150:151]
	s_waitcnt lgkmcnt(0)
	v_mfma_f32_16x16x32_bf16 v[154:157], v[2:5], v[158:161], v[154:157]
	v_lshl_add_u64 v[150:151], v[78:79], 0, v[150:151]
	v_mfma_f32_16x16x32_bf16 v[146:149], v[6:9], v[158:161], v[146:149]
	s_nop 5
	v_cvt_pk_bf16_f32 v152, v154, v155
	v_cvt_pk_bf16_f32 v153, v156, v157
	v_cvt_pk_bf16_f32 v146, v146, v147
	v_cvt_pk_bf16_f32 v147, v148, v149
	global_store_dwordx2 v[150:151], v[152:153], off
	global_store_dwordx2 v[150:151], v[146:147], off offset:2048
	ds_read_b128 v[146:149], v145 offset:4352
	ds_read_b128 v[150:153], v145 offset:39168
	s_waitcnt lgkmcnt(1)
; __device__ __forceinline__ unsigned cvt_pk_bf16(float lo, float hi) { const f2_t v = {lo, hi}; const bf2_t b = __builtin_convertvector(v, bf2_t); return __builtin_bit_cast(unsigned, b); }
; __device__ __forceinline__ f32x4 mfma16(bf16x8 a, bf16x8 b, f32x4 c) { return __builtin_amdgcn_mfma_f32_16x16x32_bf16(a, b, c, 0, 0, 0); }
; __device__ void fft2_phase(int wv, const Params& p, unsigned char* lds) {
;     ...
; #pragma unroll
;         for (int i = 0; i < 8; ++i) { f32x4 re = {0, 0, 0, 0}, im = {0, 0, 0, 0};
; #pragma unroll
;             for (int kk = 0; kk < 4; ++kk) { const bf16x8 cf = *(const bf16x8*)(CT + (16 * i + lr) * PW + 32 * kk + 8 * lq), sf = *(const bf16x8*)(ST + (16 * i + lr) * PW + 32 * kk + 8 * lq);
;                 re = mfma16(xr[kk], cf, re); re = mfma16(xi[kk], sf, re); im = mfma16(xi[kk], cf, im); im = mfma16(nxr[kk], sf, im); }
;             const int kb = 16 * i + lr;
;             bf16_t* op = Y + (sbase + (size_t)N1 * kb + ka) * 2048 + cb * 128 + 16 * w + 4 * lq;
;             u32x2 o; o.x = cvt_pk_bf16(re[0], re[1]); o.y = cvt_pk_bf16(re[2], re[3]); *(u32x2*)op = o;
;             o.x = cvt_pk_bf16(im[0], im[1]); o.y = cvt_pk_bf16(im[2], im[3]); *(u32x2*)(op + 1024) = o; }
	v_mfma_f32_16x16x32_bf16 v[154:157], v[46:49], v[146:149], 0
	v_mfma_f32_16x16x32_bf16 v[146:149], v[38:41], v[146:149], 0
	s_waitcnt lgkmcnt(0)
	v_mfma_f32_16x16x32_bf16 v[154:157], v[38:41], v[150:153], v[154:157]
	v_mfma_f32_16x16x32_bf16 v[146:149], v[42:45], v[150:153], v[146:149]
	ds_read_b128 v[150:153], v145 offset:4416
	ds_read_b128 v[158:161], v145 offset:39232
	s_waitcnt lgkmcnt(1)
	v_mfma_f32_16x16x32_bf16 v[154:157], v[34:37], v[150:153], v[154:157]
	v_mfma_f32_16x16x32_bf16 v[146:149], v[30:33], v[150:153], v[146:149]
	s_waitcnt lgkmcnt(0)
	v_mfma_f32_16x16x32_bf16 v[154:157], v[30:33], v[158:161], v[154:157]
	v_mfma_f32_16x16x32_bf16 v[146:149], v[26:29], v[158:161], v[146:149]
	ds_read_b128 v[150:153], v145 offset:4480
	ds_read_b128 v[158:161], v145 offset:39296
	s_waitcnt lgkmcnt(1)
	v_mfma_f32_16x16x32_bf16 v[154:157], v[22:25], v[150:153], v[154:157]
	v_mfma_f32_16x16x32_bf16 v[146:149], v[14:17], v[150:153], v[146:149]
	s_waitcnt lgkmcnt(0)
	v_mfma_f32_16x16x32_bf16 v[154:157], v[14:17], v[158:161], v[154:157]
	v_mfma_f32_16x16x32_bf16 v[146:149], v[18:21], v[158:161], v[146:149]
	ds_read_b128 v[150:153], v145 offset:4544
	ds_read_b128 v[158:161], v145 offset:39360
	s_waitcnt lgkmcnt(1)
	v_mfma_f32_16x16x32_bf16 v[154:157], v[10:13], v[150:153], v[154:157]
	v_mfma_f32_16x16x32_bf16 v[146:149], v[2:5], v[150:153], v[146:149]
	v_lshlrev_b64 v[150:151], s10, v[64:65]
	v_lshl_add_u64 v[150:151], s[0:1], 0, v[150:151]
	v_lshlrev_b64 v[150:151], 12, v[150:151]
	s_waitcnt lgkmcnt(0)
	v_mfma_f32_16x16x32_bf16 v[154:157], v[2:5], v[158:161], v[154:157]
	v_lshl_add_u64 v[150:151], v[78:79], 0, v[150:151]
	v_mfma_f32_16x16x32_bf16 v[146:149], v[6:9], v[158:161], v[146:149]
	s_nop 5
	v_cvt_pk_bf16_f32 v152, v154, v155
	v_cvt_pk_bf16_f32 v153, v156, v157
	v_cvt_pk_bf16_f32 v146, v146, v147
	v_cvt_pk_bf16_f32 v147, v148, v149
	global_store_dwordx2 v[150:151], v[152:153], off
	global_store_dwordx2 v[150:151], v[146:147], off offset:2048
	ds_read_b128 v[146:149], v145 offset:8704
	ds_read_b128 v[150:153], v145 offset:43520
	s_waitcnt lgkmcnt(1)
	v_mfma_f32_16x16x32_bf16 v[154:157], v[46:49], v[146:149], 0
	v_mfma_f32_16x16x32_bf16 v[146:149], v[38:41], v[146:149], 0
	s_waitcnt lgkmcnt(0)
	v_mfma_f32_16x16x32_bf16 v[154:157], v[38:41], v[150:153], v[154:157]
	v_mfma_f32_16x16x32_bf16 v[146:149], v[42:45], v[150:153], v[146:149]
	ds_read_b128 v[150:153], v145 offset:8768
	ds_read_b128 v[158:161], v145 offset:43584
	s_waitcnt lgkmcnt(1)
	v_mfma_f32_16x16x32_bf16 v[154:157], v[34:37], v[150:153], v[154:157]
	v_mfma_f32_16x16x32_bf16 v[146:149], v[30:33], v[150:153], v[146:149]
	s_waitcnt lgkmcnt(0)
	v_mfma_f32_16x16x32_bf16 v[154:157], v[30:33], v[158:161], v[154:157]
	v_mfma_f32_16x16x32_bf16 v[146:149], v[26:29], v[158:161], v[146:149]
	ds_read_b128 v[150:153], v145 offset:8832
	ds_read_b128 v[158:161], v145 offset:43648
	s_waitcnt lgkmcnt(1)
	v_mfma_f32_16x16x32_bf16 v[154:157], v[22:25], v[150:153], v[154:157]
	v_mfma_f32_16x16x32_bf16 v[146:149], v[14:17], v[150:153], v[146:149]
	s_waitcnt lgkmcnt(0)
	v_mfma_f32_16x16x32_bf16 v[154:157], v[14:17], v[158:161], v[154:157]
	v_mfma_f32_16x16x32_bf16 v[146:149], v[18:21], v[158:161], v[146:149]
	ds_read_b128 v[150:153], v145 offset:8896
	ds_read_b128 v[158:161], v145 offset:43712
	s_waitcnt lgkmcnt(1)
	v_mfma_f32_16x16x32_bf16 v[154:157], v[10:13], v[150:153], v[154:157]
	v_mfma_f32_16x16x32_bf16 v[146:149], v[2:5], v[150:153], v[146:149]
	v_lshlrev_b64 v[150:151], s10, v[66:67]
	v_lshl_add_u64 v[150:151], s[0:1], 0, v[150:151]
	v_lshlrev_b64 v[150:151], 12, v[150:151]
	s_waitcnt lgkmcnt(0)
	v_mfma_f32_16x16x32_bf16 v[154:157], v[2:5], v[158:161], v[154:157]
	v_lshl_add_u64 v[150:151], v[78:79], 0, v[150:151]
	v_mfma_f32_16x16x32_bf16 v[146:149], v[6:9], v[158:161], v[146:149]
	s_nop 5
	v_cvt_pk_bf16_f32 v152, v154, v155
	v_cvt_pk_bf16_f32 v153, v156, v157
	v_cvt_pk_bf16_f32 v146, v146, v147
	v_cvt_pk_bf16_f32 v147, v148, v149
	global_store_dwordx2 v[150:151], v[152:153], off
	global_store_dwordx2 v[150:151], v[146:147], off offset:2048
	ds_read_b128 v[146:149], v145 offset:13056
	ds_read_b128 v[150:153], v145 offset:47872
	s_waitcnt lgkmcnt(1)
	v_mfma_f32_16x16x32_bf16 v[154:157], v[46:49], v[146:149], 0
	v_mfma_f32_16x16x32_bf16 v[146:149], v[38:41], v[146:149], 0
	s_waitcnt lgkmcnt(0)
	v_mfma_f32_16x16x32_bf16 v[154:157], v[38:41], v[150:153], v[154:157]
	v_mfma_f32_16x16x32_bf16 v[146:149], v[42:45], v[150:153], v[146:149]
	ds_read_b128 v[150:153], v145 offset:13120
	ds_read_b128 v[158:161], v145 offset:47936
	s_waitcnt lgkmcnt(1)
	v_mfma_f32_16x16x32_bf16 v[154:157], v[34:37], v[150:153], v[154:157]
	v_mfma_f32_16x16x32_bf16 v[146:149], v[30:33], v[150:153], v[146:149]
	s_waitcnt lgkmcnt(0)
	v_mfma_f32_16x16x32_bf16 v[154:157], v[30:33], v[158:161], v[154:157]
	v_mfma_f32_16x16x32_bf16 v[146:149], v[26:29], v[158:161], v[146:149]
	ds_read_b128 v[150:153], v145 offset:13184
	ds_read_b128 v[158:161], v145 offset:48000
	s_waitcnt lgkmcnt(1)
	v_mfma_f32_16x16x32_bf16 v[154:157], v[22:25], v[150:153], v[154:157]
	v_mfma_f32_16x16x32_bf16 v[146:149], v[14:17], v[150:153], v[146:149]
	s_waitcnt lgkmcnt(0)
	v_mfma_f32_16x16x32_bf16 v[154:157], v[14:17], v[158:161], v[154:157]
	v_mfma_f32_16x16x32_bf16 v[146:149], v[18:21], v[158:161], v[146:149]
	ds_read_b128 v[150:153], v145 offset:13248
	ds_read_b128 v[158:161], v145 offset:48064
	s_waitcnt lgkmcnt(1)
	v_mfma_f32_16x16x32_bf16 v[154:157], v[10:13], v[150:153], v[154:157]
	v_mfma_f32_16x16x32_bf16 v[146:149], v[2:5], v[150:153], v[146:149]
	v_lshlrev_b64 v[150:151], s10, v[68:69]
	v_lshl_add_u64 v[150:151], s[0:1], 0, v[150:151]
	v_lshlrev_b64 v[150:151], 12, v[150:151]
	s_waitcnt lgkmcnt(0)
; __device__ __forceinline__ unsigned cvt_pk_bf16(float lo, float hi) { const f2_t v = {lo, hi}; const bf2_t b = __builtin_convertvector(v, bf2_t); return __builtin_bit_cast(unsigned, b); }
; __device__ __forceinline__ f32x4 mfma16(bf16x8 a, bf16x8 b, f32x4 c) { return __builtin_amdgcn_mfma_f32_16x16x32_bf16(a, b, c, 0, 0, 0); }
; __device__ void fft2_phase(int wv, const Params& p, unsigned char* lds) {
;     ...
;         for (int i = 0; i < 8; ++i) { f32x4 re = {0, 0, 0, 0}, im = {0, 0, 0, 0};
; #pragma unroll
;             for (int kk = 0; kk < 4; ++kk) { const bf16x8 cf = *(const bf16x8*)(CT + (16 * i + lr) * PW + 32 * kk + 8 * lq), sf = *(const bf16x8*)(ST + (16 * i + lr) * PW + 32 * kk + 8 * lq);
;                 re = mfma16(xr[kk], cf, re); re = mfma16(xi[kk], sf, re); im = mfma16(xi[kk], cf, im); im = mfma16(nxr[kk], sf, im); }
;             const int kb = 16 * i + lr;
;             bf16_t* op = Y + (sbase + (size_t)N1 * kb + ka) * 2048 + cb * 128 + 16 * w + 4 * lq;
;             u32x2 o; o.x = cvt_pk_bf16(re[0], re[1]); o.y = cvt_pk_bf16(re[2], re[3]); *(u32x2*)op = o;
;             o.x = cvt_pk_bf16(im[0], im[1]); o.y = cvt_pk_bf16(im[2], im[3]); *(u32x2*)(op + 1024) = o; }
	v_mfma_f32_16x16x32_bf16 v[154:157], v[2:5], v[158:161], v[154:157]
	v_lshl_add_u64 v[150:151], v[78:79], 0, v[150:151]
	v_mfma_f32_16x16x32_bf16 v[146:149], v[6:9], v[158:161], v[146:149]
	s_nop 5
	v_cvt_pk_bf16_f32 v152, v154, v155
	v_cvt_pk_bf16_f32 v153, v156, v157
	v_cvt_pk_bf16_f32 v146, v146, v147
	v_cvt_pk_bf16_f32 v147, v148, v149
	global_store_dwordx2 v[150:151], v[152:153], off
	global_store_dwordx2 v[150:151], v[146:147], off offset:2048
	ds_read_b128 v[146:149], v145 offset:17408
	ds_read_b128 v[150:153], v145 offset:52224
	s_waitcnt lgkmcnt(1)
	v_mfma_f32_16x16x32_bf16 v[154:157], v[46:49], v[146:149], 0
	v_mfma_f32_16x16x32_bf16 v[146:149], v[38:41], v[146:149], 0
	s_waitcnt lgkmcnt(0)
	v_mfma_f32_16x16x32_bf16 v[154:157], v[38:41], v[150:153], v[154:157]
	v_mfma_f32_16x16x32_bf16 v[146:149], v[42:45], v[150:153], v[146:149]
	ds_read_b128 v[150:153], v145 offset:17472
	ds_read_b128 v[158:161], v145 offset:52288
	s_waitcnt lgkmcnt(1)
	v_mfma_f32_16x16x32_bf16 v[154:157], v[34:37], v[150:153], v[154:157]
	v_mfma_f32_16x16x32_bf16 v[146:149], v[30:33], v[150:153], v[146:149]
	s_waitcnt lgkmcnt(0)
	v_mfma_f32_16x16x32_bf16 v[154:157], v[30:33], v[158:161], v[154:157]
	v_mfma_f32_16x16x32_bf16 v[146:149], v[26:29], v[158:161], v[146:149]
	ds_read_b128 v[150:153], v145 offset:17536
	ds_read_b128 v[158:161], v145 offset:52352
	s_waitcnt lgkmcnt(1)
	v_mfma_f32_16x16x32_bf16 v[154:157], v[22:25], v[150:153], v[154:157]
	v_mfma_f32_16x16x32_bf16 v[146:149], v[14:17], v[150:153], v[146:149]
	s_waitcnt lgkmcnt(0)
	v_mfma_f32_16x16x32_bf16 v[154:157], v[14:17], v[158:161], v[154:157]
	v_mfma_f32_16x16x32_bf16 v[146:149], v[18:21], v[158:161], v[146:149]
	ds_read_b128 v[150:153], v145 offset:17600
	ds_read_b128 v[158:161], v145 offset:52416
	s_waitcnt lgkmcnt(1)
	v_mfma_f32_16x16x32_bf16 v[154:157], v[10:13], v[150:153], v[154:157]
	v_mfma_f32_16x16x32_bf16 v[146:149], v[2:5], v[150:153], v[146:149]
	v_lshlrev_b64 v[150:151], s10, v[70:71]
	v_lshl_add_u64 v[150:151], s[0:1], 0, v[150:151]
	v_lshlrev_b64 v[150:151], 12, v[150:151]
	s_waitcnt lgkmcnt(0)
	v_mfma_f32_16x16x32_bf16 v[154:157], v[2:5], v[158:161], v[154:157]
	v_lshl_add_u64 v[150:151], v[78:79], 0, v[150:151]
	v_mfma_f32_16x16x32_bf16 v[146:149], v[6:9], v[158:161], v[146:149]
	s_nop 5
	v_cvt_pk_bf16_f32 v152, v154, v155
	v_cvt_pk_bf16_f32 v153, v156, v157
	v_cvt_pk_bf16_f32 v146, v146, v147
	v_cvt_pk_bf16_f32 v147, v148, v149
	global_store_dwordx2 v[150:151], v[152:153], off
	global_store_dwordx2 v[150:151], v[146:147], off offset:2048
	ds_read_b128 v[146:149], v145 offset:21760
	ds_read_b128 v[150:153], v145 offset:56576
	s_waitcnt lgkmcnt(1)
	v_mfma_f32_16x16x32_bf16 v[154:157], v[46:49], v[146:149], 0
	v_mfma_f32_16x16x32_bf16 v[146:149], v[38:41], v[146:149], 0
	s_waitcnt lgkmcnt(0)
	v_mfma_f32_16x16x32_bf16 v[154:157], v[38:41], v[150:153], v[154:157]
	v_mfma_f32_16x16x32_bf16 v[146:149], v[42:45], v[150:153], v[146:149]
	ds_read_b128 v[150:153], v145 offset:21824
	ds_read_b128 v[158:161], v145 offset:56640
	s_waitcnt lgkmcnt(1)
	v_mfma_f32_16x16x32_bf16 v[154:157], v[34:37], v[150:153], v[154:157]
	v_mfma_f32_16x16x32_bf16 v[146:149], v[30:33], v[150:153], v[146:149]
	s_waitcnt lgkmcnt(0)
	v_mfma_f32_16x16x32_bf16 v[154:157], v[30:33], v[158:161], v[154:157]
	v_mfma_f32_16x16x32_bf16 v[146:149], v[26:29], v[158:161], v[146:149]
	ds_read_b128 v[150:153], v145 offset:21888
	ds_read_b128 v[158:161], v145 offset:56704
	s_waitcnt lgkmcnt(1)
	v_mfma_f32_16x16x32_bf16 v[154:157], v[22:25], v[150:153], v[154:157]
	v_mfma_f32_16x16x32_bf16 v[146:149], v[14:17], v[150:153], v[146:149]
	s_waitcnt lgkmcnt(0)
	v_mfma_f32_16x16x32_bf16 v[154:157], v[14:17], v[158:161], v[154:157]
	v_mfma_f32_16x16x32_bf16 v[146:149], v[18:21], v[158:161], v[146:149]
	ds_read_b128 v[150:153], v145 offset:21952
	ds_read_b128 v[158:161], v145 offset:56768
	s_waitcnt lgkmcnt(1)
	v_mfma_f32_16x16x32_bf16 v[154:157], v[10:13], v[150:153], v[154:157]
	v_mfma_f32_16x16x32_bf16 v[146:149], v[2:5], v[150:153], v[146:149]
	v_lshlrev_b64 v[150:151], s10, v[72:73]
	v_lshl_add_u64 v[150:151], s[0:1], 0, v[150:151]
	v_lshlrev_b64 v[150:151], 12, v[150:151]
	s_waitcnt lgkmcnt(0)
; __device__ __forceinline__ unsigned cvt_pk_bf16(float lo, float hi) { const f2_t v = {lo, hi}; const bf2_t b = __builtin_convertvector(v, bf2_t); return __builtin_bit_cast(unsigned, b); }
; __device__ __forceinline__ f32x4 mfma16(bf16x8 a, bf16x8 b, f32x4 c) { return __builtin_amdgcn_mfma_f32_16x16x32_bf16(a, b, c, 0, 0, 0); }
; __device__ void fft2_phase(int wv, const Params& p, unsigned char* lds) {
;     ...
;         for (int i = 0; i < 8; ++i) { f32x4 re = {0, 0, 0, 0}, im = {0, 0, 0, 0};
; #pragma unroll
;             for (int kk = 0; kk < 4; ++kk) { const bf16x8 cf = *(const bf16x8*)(CT + (16 * i + lr) * PW + 32 * kk + 8 * lq), sf = *(const bf16x8*)(ST + (16 * i + lr) * PW + 32 * kk + 8 * lq);
;                 re = mfma16(xr[kk], cf, re); re = mfma16(xi[kk], sf, re); im = mfma16(xi[kk], cf, im); im = mfma16(nxr[kk], sf, im); }
;             const int kb = 16 * i + lr;
;             bf16_t* op = Y + (sbase + (size_t)N1 * kb + ka) * 2048 + cb * 128 + 16 * w + 4 * lq;
;             u32x2 o; o.x = cvt_pk_bf16(re[0], re[1]); o.y = cvt_pk_bf16(re[2], re[3]); *(u32x2*)op = o;
;             o.x = cvt_pk_bf16(im[0], im[1]); o.y = cvt_pk_bf16(im[2], im[3]); *(u32x2*)(op + 1024) = o; }
;         __syncthreads();
;     }
	v_mfma_f32_16x16x32_bf16 v[154:157], v[2:5], v[158:161], v[154:157]
	v_lshl_add_u64 v[150:151], v[78:79], 0, v[150:151]
	v_mfma_f32_16x16x32_bf16 v[146:149], v[6:9], v[158:161], v[146:149]
	s_nop 5
	v_cvt_pk_bf16_f32 v152, v154, v155
	v_cvt_pk_bf16_f32 v153, v156, v157
	v_cvt_pk_bf16_f32 v146, v146, v147
	v_cvt_pk_bf16_f32 v147, v148, v149
	global_store_dwordx2 v[150:151], v[152:153], off
	global_store_dwordx2 v[150:151], v[146:147], off offset:2048
	ds_read_b128 v[146:149], v145 offset:26112
	ds_read_b128 v[150:153], v145 offset:60928
	s_waitcnt lgkmcnt(1)
	v_mfma_f32_16x16x32_bf16 v[154:157], v[46:49], v[146:149], 0
	v_mfma_f32_16x16x32_bf16 v[146:149], v[38:41], v[146:149], 0
	s_waitcnt lgkmcnt(0)
	v_mfma_f32_16x16x32_bf16 v[154:157], v[38:41], v[150:153], v[154:157]
	v_mfma_f32_16x16x32_bf16 v[146:149], v[42:45], v[150:153], v[146:149]
	ds_read_b128 v[150:153], v145 offset:26176
	ds_read_b128 v[158:161], v145 offset:60992
	s_waitcnt lgkmcnt(1)
	v_mfma_f32_16x16x32_bf16 v[154:157], v[34:37], v[150:153], v[154:157]
	v_mfma_f32_16x16x32_bf16 v[146:149], v[30:33], v[150:153], v[146:149]
	s_waitcnt lgkmcnt(0)
	v_mfma_f32_16x16x32_bf16 v[154:157], v[30:33], v[158:161], v[154:157]
	v_mfma_f32_16x16x32_bf16 v[146:149], v[26:29], v[158:161], v[146:149]
	ds_read_b128 v[150:153], v145 offset:26240
	ds_read_b128 v[158:161], v145 offset:61056
	s_waitcnt lgkmcnt(1)
	v_mfma_f32_16x16x32_bf16 v[154:157], v[22:25], v[150:153], v[154:157]
	v_mfma_f32_16x16x32_bf16 v[146:149], v[14:17], v[150:153], v[146:149]
	s_waitcnt lgkmcnt(0)
	v_mfma_f32_16x16x32_bf16 v[154:157], v[14:17], v[158:161], v[154:157]
	v_mfma_f32_16x16x32_bf16 v[146:149], v[18:21], v[158:161], v[146:149]
	ds_read_b128 v[150:153], v145 offset:26304
	ds_read_b128 v[158:161], v145 offset:61120
	s_waitcnt lgkmcnt(1)
	v_mfma_f32_16x16x32_bf16 v[154:157], v[10:13], v[150:153], v[154:157]
	v_mfma_f32_16x16x32_bf16 v[146:149], v[2:5], v[150:153], v[146:149]
	v_lshlrev_b64 v[150:151], s10, v[74:75]
	v_lshl_add_u64 v[150:151], s[0:1], 0, v[150:151]
	v_lshlrev_b64 v[150:151], 12, v[150:151]
	s_waitcnt lgkmcnt(0)
	v_mfma_f32_16x16x32_bf16 v[154:157], v[2:5], v[158:161], v[154:157]
	v_lshl_add_u64 v[150:151], v[78:79], 0, v[150:151]
	v_mfma_f32_16x16x32_bf16 v[146:149], v[6:9], v[158:161], v[146:149]
	s_nop 5
	v_cvt_pk_bf16_f32 v152, v154, v155
	v_cvt_pk_bf16_f32 v153, v156, v157
	v_cvt_pk_bf16_f32 v146, v146, v147
	v_cvt_pk_bf16_f32 v147, v148, v149
	global_store_dwordx2 v[150:151], v[152:153], off
	global_store_dwordx2 v[150:151], v[146:147], off offset:2048
	ds_read_b128 v[146:149], v145 offset:30464
	ds_read_b128 v[150:153], v145 offset:65280
	s_waitcnt lgkmcnt(1)
	v_mfma_f32_16x16x32_bf16 v[46:49], v[46:49], v[146:149], 0
	s_waitcnt lgkmcnt(0)
	v_mfma_f32_16x16x32_bf16 v[46:49], v[38:41], v[150:153], v[46:49]
	v_mfma_f32_16x16x32_bf16 v[38:41], v[38:41], v[146:149], 0
	v_mfma_f32_16x16x32_bf16 v[38:41], v[42:45], v[150:153], v[38:41]
	ds_read_b128 v[42:45], v145 offset:30528
	ds_read_b128 v[146:149], v145 offset:65344
	s_waitcnt lgkmcnt(1)
	v_mfma_f32_16x16x32_bf16 v[34:37], v[34:37], v[42:45], v[46:49]
	s_waitcnt lgkmcnt(0)
	v_mfma_f32_16x16x32_bf16 v[34:37], v[30:33], v[146:149], v[34:37]
	v_mfma_f32_16x16x32_bf16 v[30:33], v[30:33], v[42:45], v[38:41]
	v_mfma_f32_16x16x32_bf16 v[26:29], v[26:29], v[146:149], v[30:33]
	s_nop 6
	ds_read_b128 v[30:33], v145 offset:30592
	ds_read_b128 v[38:41], v145 offset:65408
	s_waitcnt lgkmcnt(1)
	v_mfma_f32_16x16x32_bf16 v[22:25], v[22:25], v[30:33], v[34:37]
	s_waitcnt lgkmcnt(0)
	v_mfma_f32_16x16x32_bf16 v[22:25], v[14:17], v[38:41], v[22:25]
	v_mfma_f32_16x16x32_bf16 v[14:17], v[14:17], v[30:33], v[26:29]
	v_mfma_f32_16x16x32_bf16 v[14:17], v[18:21], v[38:41], v[14:17]
	ds_read_b128 v[18:21], v145 offset:30656
	s_nop 0
	ds_read_b128 v[26:29], v145 offset:65472
	s_waitcnt lgkmcnt(1)
	v_mfma_f32_16x16x32_bf16 v[10:13], v[10:13], v[18:21], v[22:25]
	s_waitcnt lgkmcnt(0)
	v_mfma_f32_16x16x32_bf16 v[10:13], v[2:5], v[26:29], v[10:13]
	v_mfma_f32_16x16x32_bf16 v[2:5], v[2:5], v[18:21], v[14:17]
	v_mfma_f32_16x16x32_bf16 v[2:5], v[6:9], v[26:29], v[2:5]
	v_lshlrev_b64 v[6:7], s10, v[76:77]
	v_lshl_add_u64 v[6:7], s[0:1], 0, v[6:7]
	v_lshlrev_b64 v[6:7], 12, v[6:7]
	v_lshl_add_u64 v[6:7], v[78:79], 0, v[6:7]
	s_nop 1
	v_cvt_pk_bf16_f32 v8, v10, v11
	v_cvt_pk_bf16_f32 v9, v12, v13
	v_cvt_pk_bf16_f32 v2, v2, v3
	v_cvt_pk_bf16_f32 v3, v4, v5
	global_store_dwordx2 v[6:7], v[8:9], off
	global_store_dwordx2 v[6:7], v[2:3], off offset:2048
	s_barrier
	s_cbranch_scc1 .LBB0_390
